# v31
# speedup vs baseline: 1.0315x; 1.0026x over previous
.LBB0_219:
	ds_read_b128 v[164:167], v160
	ds_read_b128 v[168:171], v160 offset:1024
	ds_read_b128 v[172:175], v160 offset:2048
	ds_read_b128 v[176:179], v160 offset:3072
	v_lshl_add_u64 v[240:241], v[144:145], 0, s[6:7]
	s_add_i32 m0, s100, 0xbf80
	ds_read_b128 v[184:187], v152
	ds_read_b128 v[190:193], v152 offset:1024
	ds_read_b128 v[194:197], v151
	ds_read_b128 v[198:201], v151 offset:1024
	ds_read_b128 v[206:209], v150
	ds_read_b128 v[212:215], v150 offset:1024
	ds_read_b128 v[216:219], v149
	ds_read_b128 v[220:223], v149 offset:1024
	global_load_lds_dwordx4 v[240:241], off offset:128
	s_add_i32 m0, s100, 0xdf80
	v_lshl_add_u64 v[242:243], v[142:143], 0, s[6:7]
	global_load_lds_dwordx4 v[242:243], off offset:128
	s_waitcnt lgkmcnt(8)
	s_barrier
	s_waitcnt lgkmcnt(0)
	v_mfma_f32_16x16x32_bf16 v[124:127], v[184:187], v[164:167], v[124:127]
	v_mfma_f32_16x16x32_bf16 v[120:123], v[184:187], v[172:175], v[120:123]
	v_mfma_f32_16x16x32_bf16 v[116:119], v[194:197], v[164:167], v[116:119]
	v_mfma_f32_16x16x32_bf16 v[112:115], v[194:197], v[172:175], v[112:115]
	v_mfma_f32_16x16x32_bf16 v[108:111], v[206:209], v[164:167], v[108:111]
	v_mfma_f32_16x16x32_bf16 v[104:107], v[206:209], v[172:175], v[104:107]
	v_mfma_f32_16x16x32_bf16 v[100:103], v[216:219], v[164:167], v[100:103]
	v_mfma_f32_16x16x32_bf16 v[96:99], v[216:219], v[172:175], v[96:99]
	v_mfma_f32_16x16x32_bf16 v[124:127], v[190:193], v[168:171], v[124:127]
	v_mfma_f32_16x16x32_bf16 v[120:123], v[190:193], v[176:179], v[120:123]
	v_mfma_f32_16x16x32_bf16 v[116:119], v[198:201], v[168:171], v[116:119]
	v_mfma_f32_16x16x32_bf16 v[112:115], v[198:201], v[176:179], v[112:115]
	v_mfma_f32_16x16x32_bf16 v[108:111], v[212:215], v[168:171], v[108:111]
	v_mfma_f32_16x16x32_bf16 v[104:107], v[212:215], v[176:179], v[104:107]
	v_mfma_f32_16x16x32_bf16 v[100:103], v[220:223], v[168:171], v[100:103]
	v_mfma_f32_16x16x32_bf16 v[96:99], v[220:223], v[176:179], v[96:99]
	s_barrier
	v_lshl_add_u64 v[244:245], v[130:131], 0, s[6:7]
	s_add_i32 m0, s101, 0xff00
	ds_read_b128 v[224:227], v159
	ds_read_b128 v[228:231], v159 offset:1024
	ds_read_b128 v[232:235], v159 offset:2048
	ds_read_b128 v[236:239], v159 offset:3072
	global_load_lds_dwordx4 v[244:245], off offset:256
	v_lshl_add_u64 v[246:247], v[132:133], 0, s[6:7]
	s_add_i32 m0, m0, 0x2000
	s_add_i32 s11, s11, 2
	global_load_lds_dwordx4 v[246:247], off offset:256
	s_barrier
	s_waitcnt lgkmcnt(0)
	v_mfma_f32_16x16x32_bf16 v[92:95], v[184:187], v[224:227], v[92:95]
	v_mfma_f32_16x16x32_bf16 v[88:91], v[184:187], v[232:235], v[88:91]
	v_mfma_f32_16x16x32_bf16 v[84:87], v[194:197], v[224:227], v[84:87]
	v_mfma_f32_16x16x32_bf16 v[80:83], v[194:197], v[232:235], v[80:83]
	v_mfma_f32_16x16x32_bf16 v[76:79], v[206:209], v[224:227], v[76:79]
	v_mfma_f32_16x16x32_bf16 v[72:75], v[206:209], v[232:235], v[72:75]
	v_mfma_f32_16x16x32_bf16 v[68:71], v[216:219], v[224:227], v[68:71]
	v_mfma_f32_16x16x32_bf16 v[64:67], v[216:219], v[232:235], v[64:67]
	v_mfma_f32_16x16x32_bf16 v[92:95], v[190:193], v[228:231], v[92:95]
	v_mfma_f32_16x16x32_bf16 v[88:91], v[190:193], v[236:239], v[88:91]
	v_mfma_f32_16x16x32_bf16 v[84:87], v[198:201], v[228:231], v[84:87]
	v_mfma_f32_16x16x32_bf16 v[80:83], v[198:201], v[236:239], v[80:83]
	v_mfma_f32_16x16x32_bf16 v[76:79], v[212:215], v[228:231], v[76:79]
	v_mfma_f32_16x16x32_bf16 v[72:75], v[212:215], v[236:239], v[72:75]
	v_mfma_f32_16x16x32_bf16 v[68:71], v[220:223], v[228:231], v[68:71]
	v_mfma_f32_16x16x32_bf16 v[64:67], v[220:223], v[236:239], v[64:67]
	v_lshl_add_u64 v[248:249], v[134:135], 0, s[6:7]
	v_lshl_add_u64 v[250:251], v[248:249], 0, s[64:65]
	s_mov_b32 m0, s100
	s_barrier
	ds_read_b128 v[184:187], v152 offset:16384
	ds_read_b128 v[190:193], v152 offset:17408
	ds_read_b128 v[194:197], v151 offset:16384
	ds_read_b128 v[198:201], v151 offset:17408
	ds_read_b128 v[206:209], v150 offset:16384
	ds_read_b128 v[212:215], v150 offset:17408
	ds_read_b128 v[216:219], v149 offset:16384
	ds_read_b128 v[220:223], v149 offset:17408
	global_load_lds_dwordx4 v[250:251], off
	s_add_i32 m0, s100, 0x1f00
	v_lshl_add_u64 v[250:251], v[136:137], 0, s[6:7]
	global_load_lds_dwordx4 v[250:251], off offset:256
	s_barrier
	s_waitcnt lgkmcnt(0)
	v_mfma_f32_16x16x32_bf16 v[60:63], v[184:187], v[164:167], v[60:63]
	v_mfma_f32_16x16x32_bf16 v[56:59], v[184:187], v[172:175], v[56:59]
	v_mfma_f32_16x16x32_bf16 v[52:55], v[194:197], v[164:167], v[52:55]
	v_mfma_f32_16x16x32_bf16 v[48:51], v[194:197], v[172:175], v[48:51]
	v_mfma_f32_16x16x32_bf16 v[44:47], v[206:209], v[164:167], v[44:47]
	v_mfma_f32_16x16x32_bf16 v[40:43], v[206:209], v[172:175], v[40:43]
	v_mfma_f32_16x16x32_bf16 v[36:39], v[216:219], v[164:167], v[36:39]
	v_mfma_f32_16x16x32_bf16 v[32:35], v[216:219], v[172:175], v[32:35]
	v_mfma_f32_16x16x32_bf16 v[60:63], v[190:193], v[168:171], v[60:63]
	v_mfma_f32_16x16x32_bf16 v[56:59], v[190:193], v[176:179], v[56:59]
	v_mfma_f32_16x16x32_bf16 v[52:55], v[198:201], v[168:171], v[52:55]
	v_mfma_f32_16x16x32_bf16 v[48:51], v[198:201], v[176:179], v[48:51]
	v_mfma_f32_16x16x32_bf16 v[44:47], v[212:215], v[168:171], v[44:47]
	v_mfma_f32_16x16x32_bf16 v[40:43], v[212:215], v[176:179], v[40:43]
	v_mfma_f32_16x16x32_bf16 v[36:39], v[220:223], v[168:171], v[36:39]
	v_mfma_f32_16x16x32_bf16 v[32:35], v[220:223], v[176:179], v[32:35]
	s_barrier
	v_lshl_add_u64 v[252:253], v[140:141], 0, s[6:7]
	s_add_i32 m0, s101, 0x13f00
	global_load_lds_dwordx4 v[252:253], off offset:256
	s_add_i32 m0, m0, 0x2000
	v_lshl_add_u64 v[188:189], v[138:139], 0, s[6:7]
	global_load_lds_dwordx4 v[188:189], off offset:256
	s_waitcnt vmcnt(6)
	s_barrier
	v_mfma_f32_16x16x32_bf16 v[28:31], v[184:187], v[224:227], v[28:31]
	v_mfma_f32_16x16x32_bf16 v[24:27], v[184:187], v[232:235], v[24:27]
	v_mfma_f32_16x16x32_bf16 v[20:23], v[194:197], v[224:227], v[20:23]
	v_mfma_f32_16x16x32_bf16 v[16:19], v[194:197], v[232:235], v[16:19]
	v_mfma_f32_16x16x32_bf16 v[12:15], v[206:209], v[224:227], v[12:15]
	v_mfma_f32_16x16x32_bf16 v[8:11], v[206:209], v[232:235], v[8:11]
	v_mfma_f32_16x16x32_bf16 v[4:7], v[216:219], v[224:227], v[4:7]
	v_mfma_f32_16x16x32_bf16 v[0:3], v[216:219], v[232:235], v[0:3]
	v_mfma_f32_16x16x32_bf16 v[28:31], v[190:193], v[228:231], v[28:31]
	v_mfma_f32_16x16x32_bf16 v[24:27], v[190:193], v[236:239], v[24:27]
	v_mfma_f32_16x16x32_bf16 v[20:23], v[198:201], v[228:231], v[20:23]
	v_mfma_f32_16x16x32_bf16 v[16:19], v[198:201], v[236:239], v[16:19]
	v_mfma_f32_16x16x32_bf16 v[12:15], v[212:215], v[228:231], v[12:15]
	v_mfma_f32_16x16x32_bf16 v[8:11], v[212:215], v[236:239], v[8:11]
	v_mfma_f32_16x16x32_bf16 v[4:7], v[220:223], v[228:231], v[4:7]
	v_mfma_f32_16x16x32_bf16 v[0:3], v[220:223], v[236:239], v[0:3]
	s_barrier
	ds_read_b128 v[164:167], v155
	ds_read_b128 v[168:171], v155 offset:1024
	ds_read_b128 v[172:175], v155 offset:2048
	ds_read_b128 v[176:179], v155 offset:3072
	s_add_i32 m0, s100, 0x3f00
	ds_read_b128 v[184:187], v152 offset:32768
	ds_read_b128 v[190:193], v152 offset:33792
	ds_read_b128 v[194:197], v151 offset:32768
	ds_read_b128 v[198:201], v151 offset:33792
	ds_read_b128 v[206:209], v150 offset:32768
	ds_read_b128 v[212:215], v150 offset:33792
	ds_read_b128 v[216:219], v149 offset:32768
	global_load_lds_dwordx4 v[240:241], off offset:256
	s_add_i32 m0, s100, 0x5f00
	ds_read_b128 v[220:223], v149 offset:33792
	global_load_lds_dwordx4 v[242:243], off offset:256
	s_waitcnt lgkmcnt(8)
	s_barrier
	s_waitcnt lgkmcnt(0)
	v_mfma_f32_16x16x32_bf16 v[124:127], v[184:187], v[164:167], v[124:127]
	v_mfma_f32_16x16x32_bf16 v[120:123], v[184:187], v[172:175], v[120:123]
	v_mfma_f32_16x16x32_bf16 v[116:119], v[194:197], v[164:167], v[116:119]
	v_mfma_f32_16x16x32_bf16 v[112:115], v[194:197], v[172:175], v[112:115]
	v_mfma_f32_16x16x32_bf16 v[108:111], v[206:209], v[164:167], v[108:111]
	v_mfma_f32_16x16x32_bf16 v[104:107], v[206:209], v[172:175], v[104:107]
	v_mfma_f32_16x16x32_bf16 v[100:103], v[216:219], v[164:167], v[100:103]
	v_mfma_f32_16x16x32_bf16 v[96:99], v[216:219], v[172:175], v[96:99]
	v_mfma_f32_16x16x32_bf16 v[124:127], v[190:193], v[168:171], v[124:127]
	v_mfma_f32_16x16x32_bf16 v[120:123], v[190:193], v[176:179], v[120:123]
	v_mfma_f32_16x16x32_bf16 v[116:119], v[198:201], v[168:171], v[116:119]
	v_mfma_f32_16x16x32_bf16 v[112:115], v[198:201], v[176:179], v[112:115]
	v_mfma_f32_16x16x32_bf16 v[108:111], v[212:215], v[168:171], v[108:111]
	v_mfma_f32_16x16x32_bf16 v[104:107], v[212:215], v[176:179], v[104:107]
	v_mfma_f32_16x16x32_bf16 v[100:103], v[220:223], v[168:171], v[100:103]
	v_mfma_f32_16x16x32_bf16 v[96:99], v[220:223], v[176:179], v[96:99]
	s_barrier
	s_add_i32 m0, s101, 0x17e80
	ds_read_b128 v[224:227], v153
	ds_read_b128 v[228:231], v153 offset:1024
	ds_read_b128 v[232:235], v153 offset:2048
	global_load_lds_dwordx4 v[244:245], off offset:384
	s_add_i32 m0, m0, 0x2000
	ds_read_b128 v[236:239], v153 offset:3072
	global_load_lds_dwordx4 v[246:247], off offset:384
	s_barrier
	s_waitcnt lgkmcnt(0)
	v_mfma_f32_16x16x32_bf16 v[92:95], v[184:187], v[224:227], v[92:95]
	v_mfma_f32_16x16x32_bf16 v[88:91], v[184:187], v[232:235], v[88:91]
	v_mfma_f32_16x16x32_bf16 v[84:87], v[194:197], v[224:227], v[84:87]
	v_mfma_f32_16x16x32_bf16 v[80:83], v[194:197], v[232:235], v[80:83]
	v_mfma_f32_16x16x32_bf16 v[76:79], v[206:209], v[224:227], v[76:79]
	v_mfma_f32_16x16x32_bf16 v[72:75], v[206:209], v[232:235], v[72:75]
	v_mfma_f32_16x16x32_bf16 v[68:71], v[216:219], v[224:227], v[68:71]
	v_mfma_f32_16x16x32_bf16 v[64:67], v[216:219], v[232:235], v[64:67]
	v_mfma_f32_16x16x32_bf16 v[92:95], v[190:193], v[228:231], v[92:95]
	v_mfma_f32_16x16x32_bf16 v[88:91], v[190:193], v[236:239], v[88:91]
	v_mfma_f32_16x16x32_bf16 v[84:87], v[198:201], v[228:231], v[84:87]
	v_mfma_f32_16x16x32_bf16 v[80:83], v[198:201], v[236:239], v[80:83]
	v_mfma_f32_16x16x32_bf16 v[76:79], v[212:215], v[228:231], v[76:79]
	v_mfma_f32_16x16x32_bf16 v[72:75], v[212:215], v[236:239], v[72:75]
	v_mfma_f32_16x16x32_bf16 v[68:71], v[220:223], v[228:231], v[68:71]
	v_mfma_f32_16x16x32_bf16 v[64:67], v[220:223], v[236:239], v[64:67]
	s_add_i32 m0, s100, 0x7e80
	s_barrier
	ds_read_b128 v[184:187], v152 offset:49152
	ds_read_b128 v[190:193], v152 offset:50176
	ds_read_b128 v[194:197], v151 offset:49152
	ds_read_b128 v[198:201], v151 offset:50176
	ds_read_b128 v[206:209], v150 offset:49152
	ds_read_b128 v[212:215], v150 offset:50176
	ds_read_b128 v[216:219], v149 offset:49152
	global_load_lds_dwordx4 v[248:249], off offset:384
	s_add_i32 m0, s100, 0x9e80
	ds_read_b128 v[220:223], v149 offset:50176
	global_load_lds_dwordx4 v[250:251], off offset:384
	s_barrier
	s_waitcnt lgkmcnt(0)
	v_mfma_f32_16x16x32_bf16 v[60:63], v[184:187], v[164:167], v[60:63]
	v_mfma_f32_16x16x32_bf16 v[56:59], v[184:187], v[172:175], v[56:59]
	v_mfma_f32_16x16x32_bf16 v[52:55], v[194:197], v[164:167], v[52:55]
	v_mfma_f32_16x16x32_bf16 v[48:51], v[194:197], v[172:175], v[48:51]
	v_mfma_f32_16x16x32_bf16 v[44:47], v[206:209], v[164:167], v[44:47]
	v_mfma_f32_16x16x32_bf16 v[40:43], v[206:209], v[172:175], v[40:43]
	v_mfma_f32_16x16x32_bf16 v[36:39], v[216:219], v[164:167], v[36:39]
	v_mfma_f32_16x16x32_bf16 v[32:35], v[216:219], v[172:175], v[32:35]
	v_mfma_f32_16x16x32_bf16 v[60:63], v[190:193], v[168:171], v[60:63]
	v_mfma_f32_16x16x32_bf16 v[56:59], v[190:193], v[176:179], v[56:59]
	v_mfma_f32_16x16x32_bf16 v[52:55], v[198:201], v[168:171], v[52:55]
	v_mfma_f32_16x16x32_bf16 v[48:51], v[198:201], v[176:179], v[48:51]
	v_mfma_f32_16x16x32_bf16 v[44:47], v[212:215], v[168:171], v[44:47]
	v_mfma_f32_16x16x32_bf16 v[40:43], v[212:215], v[176:179], v[40:43]
	v_mfma_f32_16x16x32_bf16 v[36:39], v[220:223], v[168:171], v[36:39]
	v_mfma_f32_16x16x32_bf16 v[32:35], v[220:223], v[176:179], v[32:35]
	s_add_i32 m0, s101, 0x1be80
	s_barrier
	global_load_lds_dwordx4 v[252:253], off offset:384
	s_add_i32 m0, m0, 0x2000
	s_add_u32 s6, s6, 0x100
	s_addc_u32 s7, s7, 0
	global_load_lds_dwordx4 v[188:189], off offset:384
	s_waitcnt vmcnt(6)
	s_barrier
	v_mfma_f32_16x16x32_bf16 v[28:31], v[184:187], v[224:227], v[28:31]
	v_mfma_f32_16x16x32_bf16 v[24:27], v[184:187], v[232:235], v[24:27]
	v_mfma_f32_16x16x32_bf16 v[20:23], v[194:197], v[224:227], v[20:23]
	v_mfma_f32_16x16x32_bf16 v[16:19], v[194:197], v[232:235], v[16:19]
	v_mfma_f32_16x16x32_bf16 v[12:15], v[206:209], v[224:227], v[12:15]
	v_mfma_f32_16x16x32_bf16 v[8:11], v[206:209], v[232:235], v[8:11]
	v_mfma_f32_16x16x32_bf16 v[4:7], v[216:219], v[224:227], v[4:7]
	v_mfma_f32_16x16x32_bf16 v[0:3], v[216:219], v[232:235], v[0:3]
	v_mfma_f32_16x16x32_bf16 v[28:31], v[190:193], v[228:231], v[28:31]
	v_mfma_f32_16x16x32_bf16 v[24:27], v[190:193], v[236:239], v[24:27]
	v_mfma_f32_16x16x32_bf16 v[20:23], v[198:201], v[228:231], v[20:23]
	v_mfma_f32_16x16x32_bf16 v[16:19], v[198:201], v[236:239], v[16:19]
	v_mfma_f32_16x16x32_bf16 v[12:15], v[212:215], v[228:231], v[12:15]
	v_mfma_f32_16x16x32_bf16 v[8:11], v[212:215], v[236:239], v[8:11]
	v_mfma_f32_16x16x32_bf16 v[4:7], v[220:223], v[228:231], v[4:7]
	v_mfma_f32_16x16x32_bf16 v[0:3], v[220:223], v[236:239], v[0:3]
	s_cmp_lt_u32 s11, s10
	s_barrier
	s_cbranch_scc1 .LBB0_219
	v_add_u32_e32 v161, 0xc000, v148
	v_add_u32_e32 v162, 0xe000, v148
	s_or_b32 s6, s60, 0x80
	s_mul_hi_u32 s7, s6, s15
	s_mul_i32 s10, s61, s15
	s_add_i32 s7, s7, s10
	s_mul_i32 s6, s6, s15
	s_lshl_b64 s[6:7], s[6:7], 1
	s_add_u32 s6, s4, s6
	s_addc_u32 s7, s5, s7
	s_add_i32 s36, s12, -1
	s_lshl_b64 s[4:5], s[36:37], 7
	s_add_u32 s4, s6, s4
	s_addc_u32 s5, s7, s5
	v_readfirstlane_b32 s6, v161
	v_lshl_add_u64 v[156:157], v[180:181], 1, s[4:5]
	s_mov_b32 m0, s6
	v_lshl_add_u64 v[128:129], v[128:129], 1, s[4:5]
	v_readfirstlane_b32 s4, v162
	ds_read_b128 v[130:133], v160
	ds_read_b128 v[134:137], v160 offset:1024
	ds_read_b128 v[138:141], v160 offset:2048
	ds_read_b128 v[142:145], v160 offset:3072
	ds_read_b128 v[164:167], v152
	ds_read_b128 v[168:171], v152 offset:1024
	ds_read_b128 v[172:175], v151
	ds_read_b128 v[176:179], v151 offset:1024
	ds_read_b128 v[184:187], v150
	ds_read_b128 v[190:193], v150 offset:1024
	ds_read_b128 v[194:197], v149
	ds_read_b128 v[198:201], v149 offset:1024
	global_load_lds_dwordx4 v[156:157], off
	s_mov_b32 m0, s4
	s_nop 0
	global_load_lds_dwordx4 v[128:129], off
	s_barrier
	s_waitcnt lgkmcnt(0)
	s_setprio 1
	s_waitcnt lgkmcnt(0)
	v_mfma_f32_16x16x32_bf16 v[124:127], v[164:167], v[130:133], v[124:127]
	v_mfma_f32_16x16x32_bf16 v[116:119], v[172:175], v[130:133], v[116:119]
	v_mfma_f32_16x16x32_bf16 v[108:111], v[184:187], v[130:133], v[108:111]
	v_mfma_f32_16x16x32_bf16 v[100:103], v[194:197], v[130:133], v[100:103]
	v_mfma_f32_16x16x32_bf16 v[124:127], v[168:171], v[134:137], v[124:127]
	v_mfma_f32_16x16x32_bf16 v[120:123], v[164:167], v[138:141], v[120:123]
	v_mfma_f32_16x16x32_bf16 v[116:119], v[176:179], v[134:137], v[116:119]
	v_mfma_f32_16x16x32_bf16 v[112:115], v[172:175], v[138:141], v[112:115]
	v_mfma_f32_16x16x32_bf16 v[108:111], v[190:193], v[134:137], v[108:111]
	v_mfma_f32_16x16x32_bf16 v[104:107], v[184:187], v[138:141], v[104:107]
	v_mfma_f32_16x16x32_bf16 v[100:103], v[198:201], v[134:137], v[100:103]
	v_mfma_f32_16x16x32_bf16 v[96:99], v[194:197], v[138:141], v[96:99]
	v_mfma_f32_16x16x32_bf16 v[160:163], v[168:171], v[142:145], v[120:123]
	v_mfma_f32_16x16x32_bf16 v[206:209], v[176:179], v[142:145], v[112:115]
	v_mfma_f32_16x16x32_bf16 v[212:215], v[190:193], v[142:145], v[104:107]
	v_mfma_f32_16x16x32_bf16 v[216:219], v[198:201], v[142:145], v[96:99]
	s_setprio 0
	s_barrier
	s_nop 1
	ds_read_b128 v[96:99], v159
	ds_read_b128 v[104:107], v159 offset:1024
	ds_read_b128 v[112:115], v159 offset:2048
	ds_read_b128 v[120:123], v159 offset:3072
	s_barrier
	s_waitcnt lgkmcnt(0)
	s_setprio 1
	s_waitcnt lgkmcnt(0)
	v_mfma_f32_16x16x32_bf16 v[92:95], v[164:167], v[96:99], v[92:95]
	v_mfma_f32_16x16x32_bf16 v[84:87], v[172:175], v[96:99], v[84:87]
	v_mfma_f32_16x16x32_bf16 v[76:79], v[184:187], v[96:99], v[76:79]
	v_mfma_f32_16x16x32_bf16 v[68:71], v[194:197], v[96:99], v[68:71]
	v_mfma_f32_16x16x32_bf16 v[92:95], v[168:171], v[104:107], v[92:95]
	v_mfma_f32_16x16x32_bf16 v[88:91], v[164:167], v[112:115], v[88:91]
	v_mfma_f32_16x16x32_bf16 v[84:87], v[176:179], v[104:107], v[84:87]
	v_mfma_f32_16x16x32_bf16 v[80:83], v[172:175], v[112:115], v[80:83]
	v_mfma_f32_16x16x32_bf16 v[76:79], v[190:193], v[104:107], v[76:79]
	v_mfma_f32_16x16x32_bf16 v[72:75], v[184:187], v[112:115], v[72:75]
	v_mfma_f32_16x16x32_bf16 v[68:71], v[198:201], v[104:107], v[68:71]
	v_mfma_f32_16x16x32_bf16 v[64:67], v[194:197], v[112:115], v[64:67]
	v_mfma_f32_16x16x32_bf16 v[156:159], v[168:171], v[120:123], v[88:91]
	v_mfma_f32_16x16x32_bf16 v[164:167], v[176:179], v[120:123], v[80:83]
	v_mfma_f32_16x16x32_bf16 v[168:171], v[190:193], v[120:123], v[72:75]
	v_mfma_f32_16x16x32_bf16 v[172:175], v[198:201], v[120:123], v[64:67]
	s_setprio 0
	s_barrier
	s_nop 1
	ds_read_b128 v[64:67], v152 offset:16384
	ds_read_b128 v[72:75], v152 offset:17408
	ds_read_b128 v[80:83], v151 offset:16384
	ds_read_b128 v[88:91], v151 offset:17408
	ds_read_b128 v[176:179], v150 offset:16384
	ds_read_b128 v[184:187], v150 offset:17408
	ds_read_b128 v[190:193], v149 offset:16384
	ds_read_b128 v[194:197], v149 offset:17408
	s_waitcnt vmcnt(4)
	s_barrier
	s_waitcnt lgkmcnt(0)
	s_setprio 1
	s_waitcnt lgkmcnt(0)
	v_mfma_f32_16x16x32_bf16 v[60:63], v[64:67], v[130:133], v[60:63]
	v_mfma_f32_16x16x32_bf16 v[52:55], v[80:83], v[130:133], v[52:55]
	v_mfma_f32_16x16x32_bf16 v[44:47], v[176:179], v[130:133], v[44:47]
	v_mfma_f32_16x16x32_bf16 v[36:39], v[190:193], v[130:133], v[36:39]
	v_mfma_f32_16x16x32_bf16 v[60:63], v[72:75], v[134:137], v[60:63]
	v_mfma_f32_16x16x32_bf16 v[56:59], v[64:67], v[138:141], v[56:59]
	v_mfma_f32_16x16x32_bf16 v[52:55], v[88:91], v[134:137], v[52:55]
	v_mfma_f32_16x16x32_bf16 v[48:51], v[80:83], v[138:141], v[48:51]
	v_mfma_f32_16x16x32_bf16 v[44:47], v[184:187], v[134:137], v[44:47]
	v_mfma_f32_16x16x32_bf16 v[40:43], v[176:179], v[138:141], v[40:43]
	v_mfma_f32_16x16x32_bf16 v[36:39], v[194:197], v[134:137], v[36:39]
	v_mfma_f32_16x16x32_bf16 v[32:35], v[190:193], v[138:141], v[32:35]
	v_mfma_f32_16x16x32_bf16 v[198:201], v[72:75], v[142:145], v[56:59]
	v_mfma_f32_16x16x32_bf16 v[220:223], v[88:91], v[142:145], v[48:51]
	v_mfma_f32_16x16x32_bf16 v[224:227], v[184:187], v[142:145], v[40:43]
	v_mfma_f32_16x16x32_bf16 v[128:131], v[194:197], v[142:145], v[32:35]
	s_setprio 0
	s_setprio 1
	v_mfma_f32_16x16x32_bf16 v[28:31], v[64:67], v[96:99], v[28:31]
	v_mfma_f32_16x16x32_bf16 v[20:23], v[80:83], v[96:99], v[20:23]
	v_mfma_f32_16x16x32_bf16 v[12:15], v[176:179], v[96:99], v[12:15]
	v_mfma_f32_16x16x32_bf16 v[4:7], v[190:193], v[96:99], v[4:7]
	v_mfma_f32_16x16x32_bf16 v[28:31], v[72:75], v[104:107], v[28:31]
	v_mfma_f32_16x16x32_bf16 v[24:27], v[64:67], v[112:115], v[24:27]
	v_mfma_f32_16x16x32_bf16 v[20:23], v[88:91], v[104:107], v[20:23]
	v_mfma_f32_16x16x32_bf16 v[16:19], v[80:83], v[112:115], v[16:19]
	v_mfma_f32_16x16x32_bf16 v[12:15], v[184:187], v[104:107], v[12:15]
	v_mfma_f32_16x16x32_bf16 v[8:11], v[176:179], v[112:115], v[8:11]
	v_mfma_f32_16x16x32_bf16 v[4:7], v[194:197], v[104:107], v[4:7]
	v_mfma_f32_16x16x32_bf16 v[0:3], v[190:193], v[112:115], v[0:3]
	v_mfma_f32_16x16x32_bf16 v[132:135], v[72:75], v[120:123], v[24:27]
	v_mfma_f32_16x16x32_bf16 v[136:139], v[88:91], v[120:123], v[16:19]
	v_mfma_f32_16x16x32_bf16 v[140:143], v[184:187], v[120:123], v[8:11]
	v_mfma_f32_16x16x32_bf16 v[176:179], v[194:197], v[120:123], v[0:3]
	s_setprio 0
	s_barrier
	s_nop 1
	ds_read_b128 v[0:3], v155
	ds_read_b128 v[8:11], v155 offset:1024
	ds_read_b128 v[16:19], v155 offset:2048
	ds_read_b128 v[24:27], v155 offset:3072
	ds_read_b128 v[32:35], v152 offset:32768
	ds_read_b128 v[40:43], v152 offset:33792
	ds_read_b128 v[48:51], v151 offset:32768
	ds_read_b128 v[56:59], v151 offset:33792
	ds_read_b128 v[64:67], v150 offset:32768
	ds_read_b128 v[184:187], v150 offset:33792
	ds_read_b128 v[190:193], v149 offset:32768
	ds_read_b128 v[194:197], v149 offset:33792
	s_waitcnt vmcnt(2)
	s_barrier
	s_waitcnt lgkmcnt(0)
	s_setprio 1
	s_waitcnt lgkmcnt(0)
	v_mfma_f32_16x16x32_bf16 v[72:75], v[32:35], v[0:3], v[124:127]
	v_mfma_f32_16x16x32_bf16 v[120:123], v[40:43], v[8:11], v[72:75]
	v_mfma_f32_16x16x32_bf16 v[72:75], v[32:35], v[16:19], v[160:163]
	v_mfma_f32_16x16x32_bf16 v[124:127], v[40:43], v[24:27], v[72:75]
	v_mfma_f32_16x16x32_bf16 v[72:75], v[48:51], v[0:3], v[116:119]
	v_mfma_f32_16x16x32_bf16 v[112:115], v[56:59], v[8:11], v[72:75]
	v_mfma_f32_16x16x32_bf16 v[72:75], v[48:51], v[16:19], v[206:209]
	v_mfma_f32_16x16x32_bf16 v[116:119], v[56:59], v[24:27], v[72:75]
	v_mfma_f32_16x16x32_bf16 v[72:75], v[64:67], v[0:3], v[108:111]
	v_mfma_f32_16x16x32_bf16 v[104:107], v[184:187], v[8:11], v[72:75]
	v_mfma_f32_16x16x32_bf16 v[72:75], v[64:67], v[16:19], v[212:215]
	v_mfma_f32_16x16x32_bf16 v[108:111], v[184:187], v[24:27], v[72:75]
	v_mfma_f32_16x16x32_bf16 v[72:75], v[190:193], v[0:3], v[100:103]
	v_mfma_f32_16x16x32_bf16 v[96:99], v[194:197], v[8:11], v[72:75]
	v_mfma_f32_16x16x32_bf16 v[72:75], v[190:193], v[16:19], v[216:219]
	v_mfma_f32_16x16x32_bf16 v[100:103], v[194:197], v[24:27], v[72:75]
	s_setprio 0
	s_barrier
	ds_read_b128 v[160:163], v153
	ds_read_b128 v[206:209], v153 offset:1024
	ds_read_b128 v[212:215], v153 offset:2048
	ds_read_b128 v[216:219], v153 offset:3072
	s_waitcnt vmcnt(0)
	s_barrier
	s_waitcnt lgkmcnt(0)
	s_setprio 1
	s_waitcnt lgkmcnt(0)
	v_mfma_f32_16x16x32_bf16 v[72:75], v[32:35], v[160:163], v[92:95]
	v_mfma_f32_16x16x32_bf16 v[32:35], v[32:35], v[212:215], v[156:159]
	v_mfma_f32_16x16x32_bf16 v[92:95], v[40:43], v[216:219], v[32:35]
	v_mfma_f32_16x16x32_bf16 v[32:35], v[48:51], v[160:163], v[84:87]
	v_mfma_f32_16x16x32_bf16 v[80:83], v[56:59], v[206:209], v[32:35]
	v_mfma_f32_16x16x32_bf16 v[32:35], v[48:51], v[212:215], v[164:167]
	v_mfma_f32_16x16x32_bf16 v[84:87], v[56:59], v[216:219], v[32:35]
	v_mfma_f32_16x16x32_bf16 v[32:35], v[64:67], v[160:163], v[76:79]
	v_mfma_f32_16x16x32_bf16 v[88:91], v[40:43], v[206:209], v[72:75]
	v_mfma_f32_16x16x32_bf16 v[72:75], v[184:187], v[206:209], v[32:35]
	v_mfma_f32_16x16x32_bf16 v[32:35], v[64:67], v[212:215], v[168:171]
	v_mfma_f32_16x16x32_bf16 v[76:79], v[184:187], v[216:219], v[32:35]
	v_mfma_f32_16x16x32_bf16 v[32:35], v[190:193], v[160:163], v[68:71]
	v_mfma_f32_16x16x32_bf16 v[64:67], v[194:197], v[206:209], v[32:35]
	v_mfma_f32_16x16x32_bf16 v[32:35], v[190:193], v[212:215], v[172:175]
	v_mfma_f32_16x16x32_bf16 v[68:71], v[194:197], v[216:219], v[32:35]
	s_setprio 0
	s_barrier
	ds_read_b128 v[154:157], v152 offset:49152
	ds_read_b128 v[164:167], v152 offset:50176
	ds_read_b128 v[168:171], v151 offset:49152
	ds_read_b128 v[172:175], v151 offset:50176
	ds_read_b128 v[184:187], v150 offset:49152
	ds_read_b128 v[150:153], v150 offset:50176
	ds_read_b128 v[190:193], v149 offset:49152
	ds_read_b128 v[194:197], v149 offset:50176
	s_barrier
	s_waitcnt lgkmcnt(0)
	s_setprio 1
	s_waitcnt lgkmcnt(0)
	v_mfma_f32_16x16x32_bf16 v[32:35], v[154:157], v[0:3], v[60:63]
	v_mfma_f32_16x16x32_bf16 v[56:59], v[164:167], v[8:11], v[32:35]
	v_mfma_f32_16x16x32_bf16 v[32:35], v[154:157], v[16:19], v[198:201]
	v_mfma_f32_16x16x32_bf16 v[60:63], v[164:167], v[24:27], v[32:35]
	v_mfma_f32_16x16x32_bf16 v[32:35], v[168:171], v[0:3], v[52:55]
	v_mfma_f32_16x16x32_bf16 v[48:51], v[172:175], v[8:11], v[32:35]
	v_mfma_f32_16x16x32_bf16 v[32:35], v[168:171], v[16:19], v[220:223]
	v_mfma_f32_16x16x32_bf16 v[52:55], v[172:175], v[24:27], v[32:35]
	v_mfma_f32_16x16x32_bf16 v[32:35], v[184:187], v[0:3], v[44:47]
	v_mfma_f32_16x16x32_bf16 v[40:43], v[150:153], v[8:11], v[32:35]
	v_mfma_f32_16x16x32_bf16 v[32:35], v[184:187], v[16:19], v[224:227]
	v_mfma_f32_16x16x32_bf16 v[0:3], v[190:193], v[0:3], v[36:39]
	v_mfma_f32_16x16x32_bf16 v[44:47], v[150:153], v[24:27], v[32:35]
	v_mfma_f32_16x16x32_bf16 v[32:35], v[194:197], v[8:11], v[0:3]
	v_mfma_f32_16x16x32_bf16 v[0:3], v[190:193], v[16:19], v[128:131]
	v_mfma_f32_16x16x32_bf16 v[36:39], v[194:197], v[24:27], v[0:3]
	s_setprio 0
	s_setprio 1
	v_mfma_f32_16x16x32_bf16 v[0:3], v[154:157], v[160:163], v[28:31]
	v_mfma_f32_16x16x32_bf16 v[24:27], v[164:167], v[206:209], v[0:3]
	v_mfma_f32_16x16x32_bf16 v[0:3], v[154:157], v[212:215], v[132:135]
	v_mfma_f32_16x16x32_bf16 v[28:31], v[164:167], v[216:219], v[0:3]
	v_mfma_f32_16x16x32_bf16 v[0:3], v[168:171], v[160:163], v[20:23]
	v_mfma_f32_16x16x32_bf16 v[16:19], v[172:175], v[206:209], v[0:3]
	v_mfma_f32_16x16x32_bf16 v[0:3], v[168:171], v[212:215], v[136:139]
	v_mfma_f32_16x16x32_bf16 v[20:23], v[172:175], v[216:219], v[0:3]
	v_mfma_f32_16x16x32_bf16 v[0:3], v[184:187], v[160:163], v[12:15]
	v_mfma_f32_16x16x32_bf16 v[8:11], v[150:153], v[206:209], v[0:3]
	v_mfma_f32_16x16x32_bf16 v[0:3], v[184:187], v[212:215], v[140:143]
	v_mfma_f32_16x16x32_bf16 v[12:15], v[150:153], v[216:219], v[0:3]
	v_mfma_f32_16x16x32_bf16 v[0:3], v[190:193], v[160:163], v[4:7]
	v_mfma_f32_16x16x32_bf16 v[4:7], v[190:193], v[212:215], v[176:179]
	v_mfma_f32_16x16x32_bf16 v[0:3], v[194:197], v[206:209], v[0:3]
	v_mfma_f32_16x16x32_bf16 v[4:7], v[194:197], v[216:219], v[4:7]
	s_setprio 0
	s_movk_i32 s4, 0x100
	v_cmp_gt_u32_e32 vcc, s4, v146
	s_barrier
	s_and_saveexec_b64 s[4:5], vcc
	s_cbranch_execz .LBB0_222
	s_barrier
